# GEMM: v031 (peel + prio flips outside the MMA barriers) + wr==1 realignment barrier moved behind the next-unit scheduling code + redundant post-barrier lgkmcnt(0) dropped (byte alignment kept with a p
# speedup vs baseline: 1.0053x; 1.0053x over previous
; #define PG8_STAGE(bufoff, gbase, voff) do { _Pragma("unroll") for (int _i = 0; _i < 2; ++_i) \
;         __builtin_amdgcn_global_load_lds((const unsigned*)((const char*)(gbase) + (voff)[_i]), (LAS unsigned*)(lds + (bufoff) + ldsw + _i * 8192), 16, 0, 0); } while (0)
; #define PG8_LDA(dst, b, h) do { _Pragma("unroll") for (int m = 0; m < 4; ++m) _Pragma("unroll") for (int k = 0; k < 2; ++k) dst[m][k] = *(const LAS bf16x8*)(lds + PG8_SA(b, h) + aoff + m * 2048 + k * 1024); } while (0)
; #define PG8_LDB(dst, b, h) do { _Pragma("unroll") for (int n = 0; n < 2; ++n) _Pragma("unroll") for (int k = 0; k < 2; ++k) dst[n][k] = *(const LAS bf16x8*)(lds + PG8_SB(b, h) + boff + n * 2048 + k * 1024); } while (0)
; #define PG8_MMA(ai, bj, At, Bt) do { __builtin_amdgcn_s_setprio(1); _Pragma("unroll") for (int m = 0; m < 4; ++m) _Pragma("unroll") for (int n = 0; n < 2; ++n) _Pragma("unroll") for (int k = 0; k < 2; ++k) \
;         acc[ai][bj][m][n] = __builtin_amdgcn_mfma_f32_16x16x32_bf16(Bt[n][k], At[m][k], acc[ai][bj][m][n], 0, 0, 0); __builtin_amdgcn_s_setprio(0); } while (0)
; __device__ __forceinline__ void gemm_phase(const int tid, LAS unsigned char* lds, const Gemm g, const StaticOrder& S, const int mode  , void* Cout, const int ldc, float* rvs, const float* rbs, const float* rbs_tail) {
;     ...
;         const bool has_next = S.next(ui + 1, nxt);
;         const char* nA = has_next ? PG8_UA(nxt) : cA; const char* nB = has_next ? PG8_UB(nxt) : cB;
;         const int ntu = cur.kc < 0 ? nt : 8;
;         for (int t = 0; t < ntu; t += 2) {
;             const bool last = (t == ntu - 2);
;             const char* a1 = cA + (size_t)(t + 1) * kstep;
;             const char* a2 = last ? nA : cA + (size_t)(t + 2) * kstep; const char* b2 = last ? nB : cB + (size_t)(t + 2) * kstep;
;             const char* a3 = a2 + kstep; const char* b3 = b2 + kstep;
;             PG8_LDB(B0, 0, 0); PG8_LDB(B1, 0, 1); PG8_SCHED; PG8_LDA(At, 0, 0); PG8_STAGE(PG8_SA(1, 1), a1 + hstepA, voffA);
;             PG8_WAIT_V(8); PG8_WAIT_L(0); PG8_BAR; PG8_MMA(0, 0, At, B0); PG8_MMA(0, 1, At, B1); PG8_BAR; PG8_SCHED;
;             PG8_LDA(At, 0, 1); PG8_STAGE(PG8_SB(0, 0), b2, voffB); PG8_STAGE(PG8_SB(0, 1), b2 + hstepB, voffB); PG8_STAGE(PG8_SA(0, 0), a2, voffA);
;             PG8_WAIT_V(8); PG8_WAIT_L(0); PG8_BAR; PG8_MMA(1, 0, At, B0); PG8_MMA(1, 1, At, B1); PG8_BAR; PG8_SCHED;
.Lgemm_nobar:
.Lgemm_peel:
	s_add_i32 s72, s68, 2
	s_add_u32 s62, s60, 0x80
	s_addc_u32 s63, s61, 0
	s_add_i32 s73, 0, 0x10000
	s_cmp_eq_u32 s33, s68
	s_cselect_b32 s63, s55, s63
	s_cselect_b32 s62, s54, s62
	v_add_u32_e32 v158, s73, v147
	s_cselect_b32 s75, s57, s53
	s_cselect_b32 s74, s56, s45
	s_add_i32 s68, 0, 0x14000
	ds_read_b128 v[142:145], v158
	ds_read_b128 v[150:153], v158 offset:1024
	ds_read_b128 v[154:157], v158 offset:2048
	ds_read_b128 v[168:171], v158 offset:3072
	v_add_u32_e32 v158, s68, v147
	ds_read_b128 v[172:175], v158
	ds_read_b128 v[176:179], v158 offset:1024
	ds_read_b128 v[180:183], v158 offset:2048
	ds_read_b128 v[184:187], v158 offset:3072
	v_lshl_add_u64 v[158:159], s[60:61], 0, v[138:139]
	s_add_i32 m0, s71, 0xc000
	ds_read_b128 v[188:191], v149
	ds_read_b128 v[212:215], v149 offset:1024
	ds_read_b128 v[216:219], v149 offset:2048
	ds_read_b128 v[220:223], v149 offset:3072
	ds_read_b128 v[224:227], v149 offset:4096
	ds_read_b128 v[228:231], v149 offset:5120
	ds_read_b128 v[232:235], v149 offset:6144
	ds_read_b128 v[236:239], v149 offset:7168
	global_load_lds_dwordx4 v[158:159], off
	v_lshl_add_u64 v[158:159], s[60:61], 0, v[140:141]
	s_add_i32 m0, s71, 0xe000
	s_nop 0
	global_load_lds_dwordx4 v[158:159], off
	s_nop 0
	s_setprio 1
	s_waitcnt vmcnt(8)
	s_waitcnt lgkmcnt(0)
	s_barrier
	v_mfma_f32_16x16x32_bf16 v[124:127], v[142:145], v[188:191], 0
	v_mfma_f32_16x16x32_bf16 v[120:123], v[154:157], v[188:191], 0
	v_mfma_f32_16x16x32_bf16 v[116:119], v[142:145], v[216:219], 0
	v_mfma_f32_16x16x32_bf16 v[112:115], v[154:157], v[216:219], 0
	v_mfma_f32_16x16x32_bf16 v[104:107], v[142:145], v[224:227], 0
	v_mfma_f32_16x16x32_bf16 v[96:99], v[154:157], v[224:227], 0
	v_mfma_f32_16x16x32_bf16 v[88:91], v[142:145], v[232:235], 0
	v_mfma_f32_16x16x32_bf16 v[80:83], v[154:157], v[232:235], 0
	v_mfma_f32_16x16x32_bf16 v[124:127], v[150:153], v[212:215], v[124:127]
	v_mfma_f32_16x16x32_bf16 v[120:123], v[168:171], v[212:215], v[120:123]
	v_mfma_f32_16x16x32_bf16 v[116:119], v[150:153], v[220:223], v[116:119]
	v_mfma_f32_16x16x32_bf16 v[112:115], v[168:171], v[220:223], v[112:115]
	v_mfma_f32_16x16x32_bf16 v[104:107], v[150:153], v[228:231], v[104:107]
	v_mfma_f32_16x16x32_bf16 v[96:99], v[168:171], v[228:231], v[96:99]
	v_mfma_f32_16x16x32_bf16 v[88:91], v[150:153], v[236:239], v[88:91]
	v_mfma_f32_16x16x32_bf16 v[80:83], v[168:171], v[236:239], v[80:83]
	s_setprio 0
	s_setprio 1
	v_mfma_f32_16x16x32_bf16 v[108:111], v[172:175], v[188:191], 0
	v_mfma_f32_16x16x32_bf16 v[100:103], v[180:183], v[188:191], 0
	v_mfma_f32_16x16x32_bf16 v[92:95], v[172:175], v[216:219], 0
	v_mfma_f32_16x16x32_bf16 v[84:87], v[180:183], v[216:219], 0
	v_mfma_f32_16x16x32_bf16 v[76:79], v[172:175], v[224:227], 0
	v_mfma_f32_16x16x32_bf16 v[72:75], v[180:183], v[224:227], 0
	v_mfma_f32_16x16x32_bf16 v[68:71], v[172:175], v[232:235], 0
	v_mfma_f32_16x16x32_bf16 v[64:67], v[180:183], v[232:235], 0
	v_mfma_f32_16x16x32_bf16 v[108:111], v[176:179], v[212:215], v[108:111]
	v_mfma_f32_16x16x32_bf16 v[100:103], v[184:187], v[212:215], v[100:103]
	v_mfma_f32_16x16x32_bf16 v[92:95], v[176:179], v[220:223], v[92:95]
	v_mfma_f32_16x16x32_bf16 v[84:87], v[184:187], v[220:223], v[84:87]
	v_mfma_f32_16x16x32_bf16 v[76:79], v[176:179], v[228:231], v[76:79]
	v_mfma_f32_16x16x32_bf16 v[72:75], v[184:187], v[228:231], v[72:75]
	v_mfma_f32_16x16x32_bf16 v[68:71], v[176:179], v[236:239], v[68:71]
	v_mfma_f32_16x16x32_bf16 v[64:67], v[184:187], v[236:239], v[64:67]
	s_barrier
	s_setprio 0
	s_add_i32 s73, s73, s70
	v_lshl_add_u64 v[158:159], s[74:75], 0, v[160:161]
	s_mov_b32 m0, s73
	ds_read_b128 v[188:191], v149 offset:16384
	ds_read_b128 v[212:215], v149 offset:17408
	ds_read_b128 v[216:219], v149 offset:18432
	ds_read_b128 v[220:223], v149 offset:19456
	ds_read_b128 v[224:227], v149 offset:20480
	ds_read_b128 v[228:231], v149 offset:21504
	ds_read_b128 v[232:235], v149 offset:22528
	ds_read_b128 v[236:239], v149 offset:23552
	global_load_lds_dwordx4 v[158:159], off
	s_add_i32 m0, s73, 0x2000
	v_lshl_add_u64 v[192:193], s[74:75], 0, v[132:133]
	s_add_u32 s74, s74, s59
	s_addc_u32 s75, s75, 0
	s_add_i32 s68, s68, s70
	global_load_lds_dwordx4 v[192:193], off
	v_lshl_add_u64 v[194:195], s[74:75], 0, v[160:161]
	s_mov_b32 m0, s68
	v_lshl_add_u64 v[240:241], s[74:75], 0, v[132:133]
	global_load_lds_dwordx4 v[194:195], off
	s_add_i32 m0, s68, 0x2000
	v_lshl_add_u64 v[242:243], s[62:63], 0, v[128:129]
	global_load_lds_dwordx4 v[240:241], off
	s_mov_b32 m0, s71
	v_lshl_add_u64 v[244:245], s[62:63], 0, v[130:131]
	global_load_lds_dwordx4 v[242:243], off
	s_mov_b32 m0, s88
	s_nop 0
	global_load_lds_dwordx4 v[244:245], off
	s_nop 0
	s_setprio 1
	s_waitcnt vmcnt(8)
	s_waitcnt lgkmcnt(0)
	s_barrier
; #define PG8_STAGE(bufoff, gbase, voff) do { _Pragma("unroll") for (int _i = 0; _i < 2; ++_i) \
;         __builtin_amdgcn_global_load_lds((const unsigned*)((const char*)(gbase) + (voff)[_i]), (LAS unsigned*)(lds + (bufoff) + ldsw + _i * 8192), 16, 0, 0); } while (0)
; #define PG8_LDA(dst, b, h) do { _Pragma("unroll") for (int m = 0; m < 4; ++m) _Pragma("unroll") for (int k = 0; k < 2; ++k) dst[m][k] = *(const LAS bf16x8*)(lds + PG8_SA(b, h) + aoff + m * 2048 + k * 1024); } while (0)
; #define PG8_LDB(dst, b, h) do { _Pragma("unroll") for (int n = 0; n < 2; ++n) _Pragma("unroll") for (int k = 0; k < 2; ++k) dst[n][k] = *(const LAS bf16x8*)(lds + PG8_SB(b, h) + boff + n * 2048 + k * 1024); } while (0)
; #define PG8_MMA(ai, bj, At, Bt) do { __builtin_amdgcn_s_setprio(1); _Pragma("unroll") for (int m = 0; m < 4; ++m) _Pragma("unroll") for (int n = 0; n < 2; ++n) _Pragma("unroll") for (int k = 0; k < 2; ++k) \
;         acc[ai][bj][m][n] = __builtin_amdgcn_mfma_f32_16x16x32_bf16(Bt[n][k], At[m][k], acc[ai][bj][m][n], 0, 0, 0); __builtin_amdgcn_s_setprio(0); } while (0)
; #define PG8_WAIT_V(n) asm volatile("s_waitcnt vmcnt(" #n ")" ::: "memory")
; #define PG8_WAIT_L(n) asm volatile("s_waitcnt lgkmcnt(" #n ")" ::: "memory")
; #define PG8_BAR __builtin_amdgcn_s_barrier()
; #define PG8_SCHED __builtin_amdgcn_sched_barrier(0)
; __device__ __forceinline__ void gemm_phase(const int tid, LAS unsigned char* lds, const Gemm g, const StaticOrder& S, const int mode  , void* Cout, const int ldc, float* rvs, const float* rbs, const float* rbs_tail) {
;     ...
;             PG8_WAIT_V(8); PG8_WAIT_L(0); PG8_BAR; PG8_MMA(1, 0, At, B0); PG8_MMA(1, 1, At, B1); PG8_BAR; PG8_SCHED;
;             PG8_LDB(B0, 1, 0); PG8_LDB(B1, 1, 1); PG8_SCHED; PG8_LDA(At, 1, 0); PG8_STAGE(PG8_SA(0, 1), a2 + hstepA, voffA);
;             PG8_WAIT_V(8); PG8_WAIT_L(0); PG8_BAR; PG8_MMA(0, 0, At, B0); PG8_MMA(0, 1, At, B1); PG8_BAR; PG8_SCHED;
	v_mfma_f32_16x16x32_bf16 v[60:63], v[142:145], v[188:191], 0
	v_mfma_f32_16x16x32_bf16 v[56:59], v[154:157], v[188:191], 0
	v_mfma_f32_16x16x32_bf16 v[52:55], v[142:145], v[216:219], 0
	v_mfma_f32_16x16x32_bf16 v[48:51], v[154:157], v[216:219], 0
	v_mfma_f32_16x16x32_bf16 v[36:39], v[142:145], v[224:227], 0
	v_mfma_f32_16x16x32_bf16 v[32:35], v[154:157], v[224:227], 0
	v_mfma_f32_16x16x32_bf16 v[20:23], v[142:145], v[232:235], 0
	v_mfma_f32_16x16x32_bf16 v[16:19], v[154:157], v[232:235], 0
	v_mfma_f32_16x16x32_bf16 v[60:63], v[150:153], v[212:215], v[60:63]
	v_mfma_f32_16x16x32_bf16 v[56:59], v[168:171], v[212:215], v[56:59]
	v_mfma_f32_16x16x32_bf16 v[52:55], v[150:153], v[220:223], v[52:55]
	v_mfma_f32_16x16x32_bf16 v[48:51], v[168:171], v[220:223], v[48:51]
	v_mfma_f32_16x16x32_bf16 v[36:39], v[150:153], v[228:231], v[36:39]
	v_mfma_f32_16x16x32_bf16 v[32:35], v[168:171], v[228:231], v[32:35]
	v_mfma_f32_16x16x32_bf16 v[20:23], v[150:153], v[236:239], v[20:23]
	v_mfma_f32_16x16x32_bf16 v[16:19], v[168:171], v[236:239], v[16:19]
	s_setprio 0
	s_setprio 1
	v_mfma_f32_16x16x32_bf16 v[44:47], v[172:175], v[188:191], 0
	v_mfma_f32_16x16x32_bf16 v[40:43], v[180:183], v[188:191], 0
	v_mfma_f32_16x16x32_bf16 v[28:31], v[172:175], v[216:219], 0
	v_mfma_f32_16x16x32_bf16 v[24:27], v[180:183], v[216:219], 0
	v_mfma_f32_16x16x32_bf16 v[12:15], v[172:175], v[224:227], 0
	v_mfma_f32_16x16x32_bf16 v[8:11], v[180:183], v[224:227], 0
	v_mfma_f32_16x16x32_bf16 v[4:7], v[172:175], v[232:235], 0
	v_mfma_f32_16x16x32_bf16 v[0:3], v[180:183], v[232:235], 0
	v_mfma_f32_16x16x32_bf16 v[44:47], v[176:179], v[212:215], v[44:47]
	v_mfma_f32_16x16x32_bf16 v[40:43], v[184:187], v[212:215], v[40:43]
	v_mfma_f32_16x16x32_bf16 v[28:31], v[176:179], v[220:223], v[28:31]
	v_mfma_f32_16x16x32_bf16 v[24:27], v[184:187], v[220:223], v[24:27]
	v_mfma_f32_16x16x32_bf16 v[12:15], v[176:179], v[228:231], v[12:15]
	v_mfma_f32_16x16x32_bf16 v[8:11], v[184:187], v[228:231], v[8:11]
	v_mfma_f32_16x16x32_bf16 v[4:7], v[176:179], v[236:239], v[4:7]
	v_mfma_f32_16x16x32_bf16 v[0:3], v[184:187], v[236:239], v[0:3]
	s_barrier
	s_setprio 0
	s_add_i32 s68, 0, 0x18000
	v_add_u32_e32 v165, s68, v147
	s_add_i32 s73, 0, 0x1c000
	ds_read_b128 v[142:145], v165
	ds_read_b128 v[150:153], v165 offset:1024
	ds_read_b128 v[154:157], v165 offset:2048
	ds_read_b128 v[168:171], v165 offset:3072
	v_add_u32_e32 v165, s73, v147
	ds_read_b128 v[172:175], v165
	ds_read_b128 v[176:179], v165 offset:1024
	ds_read_b128 v[180:183], v165 offset:2048
	ds_read_b128 v[184:187], v165 offset:3072
	s_add_u32 s62, s62, s46
	s_addc_u32 s63, s63, 0
	s_mov_b32 m0, s89
	v_lshl_add_u64 v[246:247], s[62:63], 0, v[128:129]
	ds_read_b128 v[188:191], v149 offset:32768
	ds_read_b128 v[212:215], v149 offset:33792
	ds_read_b128 v[216:219], v149 offset:34816
	ds_read_b128 v[220:223], v149 offset:35840
	ds_read_b128 v[224:227], v149 offset:36864
	ds_read_b128 v[228:231], v149 offset:37888
	ds_read_b128 v[232:235], v149 offset:38912
	ds_read_b128 v[236:239], v149 offset:39936
	global_load_lds_dwordx4 v[246:247], off
	v_lshl_add_u64 v[246:247], s[62:63], 0, v[130:131]
	s_mov_b32 m0, s90
	s_nop 0
	global_load_lds_dwordx4 v[246:247], off
	s_nop 0
	s_setprio 1
	s_waitcnt vmcnt(8)
	s_waitcnt lgkmcnt(0)
	s_barrier
	v_mfma_f32_16x16x32_bf16 v[124:127], v[142:145], v[188:191], v[124:127]
	v_mfma_f32_16x16x32_bf16 v[120:123], v[154:157], v[188:191], v[120:123]
	v_mfma_f32_16x16x32_bf16 v[116:119], v[142:145], v[216:219], v[116:119]
	v_mfma_f32_16x16x32_bf16 v[112:115], v[154:157], v[216:219], v[112:115]
	v_mfma_f32_16x16x32_bf16 v[104:107], v[142:145], v[224:227], v[104:107]
	v_mfma_f32_16x16x32_bf16 v[96:99], v[154:157], v[224:227], v[96:99]
	v_mfma_f32_16x16x32_bf16 v[88:91], v[142:145], v[232:235], v[88:91]
	v_mfma_f32_16x16x32_bf16 v[80:83], v[154:157], v[232:235], v[80:83]
	v_mfma_f32_16x16x32_bf16 v[124:127], v[150:153], v[212:215], v[124:127]
	v_mfma_f32_16x16x32_bf16 v[120:123], v[168:171], v[212:215], v[120:123]
	v_mfma_f32_16x16x32_bf16 v[116:119], v[150:153], v[220:223], v[116:119]
	v_mfma_f32_16x16x32_bf16 v[112:115], v[168:171], v[220:223], v[112:115]
	v_mfma_f32_16x16x32_bf16 v[104:107], v[150:153], v[228:231], v[104:107]
	v_mfma_f32_16x16x32_bf16 v[96:99], v[168:171], v[228:231], v[96:99]
	v_mfma_f32_16x16x32_bf16 v[88:91], v[150:153], v[236:239], v[88:91]
	v_mfma_f32_16x16x32_bf16 v[80:83], v[168:171], v[236:239], v[80:83]
	s_setprio 0
	s_setprio 1
	v_mfma_f32_16x16x32_bf16 v[108:111], v[172:175], v[188:191], v[108:111]
	v_mfma_f32_16x16x32_bf16 v[100:103], v[180:183], v[188:191], v[100:103]
	v_mfma_f32_16x16x32_bf16 v[92:95], v[172:175], v[216:219], v[92:95]
	v_mfma_f32_16x16x32_bf16 v[84:87], v[180:183], v[216:219], v[84:87]
	v_mfma_f32_16x16x32_bf16 v[76:79], v[172:175], v[224:227], v[76:79]
	v_mfma_f32_16x16x32_bf16 v[72:75], v[180:183], v[224:227], v[72:75]
	v_mfma_f32_16x16x32_bf16 v[68:71], v[172:175], v[232:235], v[68:71]
	v_mfma_f32_16x16x32_bf16 v[64:67], v[180:183], v[232:235], v[64:67]
	v_mfma_f32_16x16x32_bf16 v[108:111], v[176:179], v[212:215], v[108:111]
	v_mfma_f32_16x16x32_bf16 v[100:103], v[184:187], v[212:215], v[100:103]
	v_mfma_f32_16x16x32_bf16 v[92:95], v[176:179], v[220:223], v[92:95]
	v_mfma_f32_16x16x32_bf16 v[84:87], v[184:187], v[220:223], v[84:87]
	v_mfma_f32_16x16x32_bf16 v[76:79], v[176:179], v[228:231], v[76:79]
	v_mfma_f32_16x16x32_bf16 v[72:75], v[184:187], v[228:231], v[72:75]
	v_mfma_f32_16x16x32_bf16 v[68:71], v[176:179], v[236:239], v[68:71]
	v_mfma_f32_16x16x32_bf16 v[64:67], v[184:187], v[236:239], v[64:67]
	s_barrier
; #define PG8_STAGE(bufoff, gbase, voff) do { _Pragma("unroll") for (int _i = 0; _i < 2; ++_i) \
;         __builtin_amdgcn_global_load_lds((const unsigned*)((const char*)(gbase) + (voff)[_i]), (LAS unsigned*)(lds + (bufoff) + ldsw + _i * 8192), 16, 0, 0); } while (0)
; #define PG8_LDA(dst, b, h) do { _Pragma("unroll") for (int m = 0; m < 4; ++m) _Pragma("unroll") for (int k = 0; k < 2; ++k) dst[m][k] = *(const LAS bf16x8*)(lds + PG8_SA(b, h) + aoff + m * 2048 + k * 1024); } while (0)
; #define PG8_LDB(dst, b, h) do { _Pragma("unroll") for (int n = 0; n < 2; ++n) _Pragma("unroll") for (int k = 0; k < 2; ++k) dst[n][k] = *(const LAS bf16x8*)(lds + PG8_SB(b, h) + boff + n * 2048 + k * 1024); } while (0)
; #define PG8_WAIT_V(n) asm volatile("s_waitcnt vmcnt(" #n ")" ::: "memory")
; __device__ __forceinline__ void gemm_phase(const int tid, LAS unsigned char* lds, const Gemm g, const StaticOrder& S, const int mode  , void* Cout, const int ldc, float* rvs, const float* rbs, const float* rbs_tail) {
;     ...
;         for (int t = 0; t < ntu; t += 2) {
;             const bool last = (t == ntu - 2);
;             const char* a1 = cA + (size_t)(t + 1) * kstep;
;             const char* a2 = last ? nA : cA + (size_t)(t + 2) * kstep; const char* b2 = last ? nB : cB + (size_t)(t + 2) * kstep;
;             const char* a3 = a2 + kstep; const char* b3 = b2 + kstep;
;             PG8_LDB(B0, 0, 0); PG8_LDB(B1, 0, 1); PG8_SCHED; PG8_LDA(At, 0, 0); PG8_STAGE(PG8_SA(1, 1), a1 + hstepA, voffA);
;             PG8_WAIT_V(8); PG8_WAIT_L(0); PG8_BAR; PG8_MMA(0, 0, At, B0); PG8_MMA(0, 1, At, B1); PG8_BAR; PG8_SCHED;
;             PG8_LDA(At, 0, 1); PG8_STAGE(PG8_SB(0, 0), b2, voffB); PG8_STAGE(PG8_SB(0, 1), b2 + hstepB, voffB); PG8_STAGE(PG8_SA(0, 0), a2, voffA);
;             PG8_WAIT_V(8); PG8_WAIT_L(0); PG8_BAR; PG8_MMA(1, 0, At, B0); PG8_MMA(1, 1, At, B1); PG8_BAR; PG8_SCHED;
;             PG8_LDB(B0, 1, 0); PG8_LDB(B1, 1, 1); PG8_SCHED; PG8_LDA(At, 1, 0); PG8_STAGE(PG8_SA(0, 1), a2 + hstepA, voffA);
;             PG8_WAIT_V(8); PG8_WAIT_L(0); PG8_BAR; PG8_MMA(0, 0, At, B0); PG8_MMA(0, 1, At, B1); PG8_BAR; PG8_SCHED;
;             PG8_LDA(At, 1, 1); PG8_STAGE(PG8_SB(1, 0), b3, voffB); PG8_STAGE(PG8_SB(1, 1), b3 + hstepB, voffB); PG8_STAGE(PG8_SA(1, 0), a3, voffA);
;             PG8_WAIT_V(8); PG8_WAIT_L(0); PG8_BAR; PG8_MMA(1, 0, At, B0); PG8_MMA(1, 1, At, B1); PG8_BAR; PG8_SCHED;
	s_setprio 0
	s_add_i32 s62, s68, s70
	v_lshl_add_u64 v[158:159], v[158:159], 0, s[36:37]
	s_mov_b32 m0, s62
	ds_read_b128 v[188:191], v149 offset:49152
	ds_read_b128 v[212:215], v149 offset:50176
	ds_read_b128 v[216:219], v149 offset:51200
	ds_read_b128 v[220:223], v149 offset:52224
	ds_read_b128 v[224:227], v149 offset:53248
	ds_read_b128 v[228:231], v149 offset:54272
	ds_read_b128 v[232:235], v149 offset:55296
	ds_read_b128 v[236:239], v149 offset:56320
	global_load_lds_dwordx4 v[158:159], off
	v_lshl_add_u64 v[158:159], v[192:193], 0, s[36:37]
	s_add_i32 m0, s62, 0x2000
	s_add_i32 s62, s73, s70
	global_load_lds_dwordx4 v[158:159], off
	v_lshl_add_u64 v[158:159], v[194:195], 0, s[36:37]
	s_mov_b32 m0, s62
	s_nop 0
	global_load_lds_dwordx4 v[158:159], off
	v_lshl_add_u64 v[158:159], v[240:241], 0, s[36:37]
	s_add_i32 m0, s62, 0x2000
	s_nop 0
	global_load_lds_dwordx4 v[158:159], off
	v_lshl_add_u64 v[158:159], v[242:243], 0, s[36:37]
	s_mov_b32 m0, s91
	s_nop 0
	global_load_lds_dwordx4 v[158:159], off
	v_lshl_add_u64 v[158:159], v[244:245], 0, s[36:37]
	s_mov_b32 m0, s16
	s_nop 0
	global_load_lds_dwordx4 v[158:159], off
	s_nop 0
	s_setprio 1
	s_waitcnt vmcnt(8)
	s_waitcnt lgkmcnt(0)
	s_barrier
	v_mfma_f32_16x16x32_bf16 v[60:63], v[142:145], v[188:191], v[60:63]
	v_mfma_f32_16x16x32_bf16 v[56:59], v[154:157], v[188:191], v[56:59]
	v_mfma_f32_16x16x32_bf16 v[52:55], v[142:145], v[216:219], v[52:55]
	v_mfma_f32_16x16x32_bf16 v[48:51], v[154:157], v[216:219], v[48:51]
	v_mfma_f32_16x16x32_bf16 v[36:39], v[142:145], v[224:227], v[36:39]
	v_mfma_f32_16x16x32_bf16 v[32:35], v[154:157], v[224:227], v[32:35]
	v_mfma_f32_16x16x32_bf16 v[20:23], v[142:145], v[232:235], v[20:23]
	v_mfma_f32_16x16x32_bf16 v[16:19], v[154:157], v[232:235], v[16:19]
	v_mfma_f32_16x16x32_bf16 v[60:63], v[150:153], v[212:215], v[60:63]
	v_mfma_f32_16x16x32_bf16 v[56:59], v[168:171], v[212:215], v[56:59]
	v_mfma_f32_16x16x32_bf16 v[52:55], v[150:153], v[220:223], v[52:55]
	v_mfma_f32_16x16x32_bf16 v[48:51], v[168:171], v[220:223], v[48:51]
	v_mfma_f32_16x16x32_bf16 v[36:39], v[150:153], v[228:231], v[36:39]
	v_mfma_f32_16x16x32_bf16 v[32:35], v[168:171], v[228:231], v[32:35]
	v_mfma_f32_16x16x32_bf16 v[20:23], v[150:153], v[236:239], v[20:23]
	v_mfma_f32_16x16x32_bf16 v[16:19], v[168:171], v[236:239], v[16:19]
	s_setprio 0
	s_setprio 1
	v_mfma_f32_16x16x32_bf16 v[44:47], v[172:175], v[188:191], v[44:47]
	v_mfma_f32_16x16x32_bf16 v[40:43], v[180:183], v[188:191], v[40:43]
	v_mfma_f32_16x16x32_bf16 v[28:31], v[172:175], v[216:219], v[28:31]
	v_mfma_f32_16x16x32_bf16 v[24:27], v[180:183], v[216:219], v[24:27]
	v_mfma_f32_16x16x32_bf16 v[12:15], v[172:175], v[224:227], v[12:15]
	v_mfma_f32_16x16x32_bf16 v[8:11], v[180:183], v[224:227], v[8:11]
	v_mfma_f32_16x16x32_bf16 v[4:7], v[172:175], v[232:235], v[4:7]
	v_mfma_f32_16x16x32_bf16 v[0:3], v[180:183], v[232:235], v[0:3]
	v_mfma_f32_16x16x32_bf16 v[44:47], v[176:179], v[212:215], v[44:47]
	v_mfma_f32_16x16x32_bf16 v[40:43], v[184:187], v[212:215], v[40:43]
	v_mfma_f32_16x16x32_bf16 v[28:31], v[176:179], v[220:223], v[28:31]
	v_mfma_f32_16x16x32_bf16 v[24:27], v[184:187], v[220:223], v[24:27]
	v_mfma_f32_16x16x32_bf16 v[12:15], v[176:179], v[228:231], v[12:15]
	v_mfma_f32_16x16x32_bf16 v[8:11], v[184:187], v[228:231], v[8:11]
	v_mfma_f32_16x16x32_bf16 v[4:7], v[176:179], v[236:239], v[4:7]
	v_mfma_f32_16x16x32_bf16 v[0:3], v[184:187], v[236:239], v[0:3]
	s_barrier
	s_setprio 0
	s_add_u32 s60, s60, 0x100
	s_addc_u32 s61, s61, 0
	s_add_u32 s45, s45, 0x100
	s_addc_u32 s53, s53, 0
	s_cmp_ge_u32 s72, s3
	s_mov_b32 s68, s72
	s_cbranch_scc0 .LBB0_231
	s_branch .Lgemm_k_done
.LBB0_231:
	s_add_i32 s72, s68, 2
	s_add_u32 s62, s60, 0x80
	s_addc_u32 s63, s61, 0
	s_add_i32 s73, 0, 0x10000
	s_cmp_eq_u32 s33, s68
	s_cselect_b32 s63, s55, s63
	s_cselect_b32 s62, s54, s62
	v_add_u32_e32 v158, s73, v147
	s_cselect_b32 s75, s57, s53
	s_cselect_b32 s74, s56, s45
	s_add_i32 s68, 0, 0x14000
	ds_read_b128 v[142:145], v158
	ds_read_b128 v[150:153], v158 offset:1024
	ds_read_b128 v[154:157], v158 offset:2048
	ds_read_b128 v[168:171], v158 offset:3072
	v_add_u32_e32 v158, s68, v147
	ds_read_b128 v[172:175], v158
	ds_read_b128 v[176:179], v158 offset:1024
	ds_read_b128 v[180:183], v158 offset:2048
	ds_read_b128 v[184:187], v158 offset:3072
	v_lshl_add_u64 v[158:159], s[60:61], 0, v[138:139]
	s_add_i32 m0, s71, 0xc000
	ds_read_b128 v[188:191], v149
	ds_read_b128 v[212:215], v149 offset:1024
	ds_read_b128 v[216:219], v149 offset:2048
	ds_read_b128 v[220:223], v149 offset:3072
	ds_read_b128 v[224:227], v149 offset:4096
	ds_read_b128 v[228:231], v149 offset:5120
	ds_read_b128 v[232:235], v149 offset:6144
	ds_read_b128 v[236:239], v149 offset:7168
	global_load_lds_dwordx4 v[158:159], off
	v_lshl_add_u64 v[158:159], s[60:61], 0, v[140:141]
	s_add_i32 m0, s71, 0xe000
	s_nop 0
	global_load_lds_dwordx4 v[158:159], off
	s_nop 0
	s_setprio 1
	s_waitcnt vmcnt(8)
	s_waitcnt lgkmcnt(0)
	s_barrier
; #define PG8_STAGE(bufoff, gbase, voff) do { _Pragma("unroll") for (int _i = 0; _i < 2; ++_i) \
;         __builtin_amdgcn_global_load_lds((const unsigned*)((const char*)(gbase) + (voff)[_i]), (LAS unsigned*)(lds + (bufoff) + ldsw + _i * 8192), 16, 0, 0); } while (0)
; #define PG8_LDA(dst, b, h) do { _Pragma("unroll") for (int m = 0; m < 4; ++m) _Pragma("unroll") for (int k = 0; k < 2; ++k) dst[m][k] = *(const LAS bf16x8*)(lds + PG8_SA(b, h) + aoff + m * 2048 + k * 1024); } while (0)
; #define PG8_MMA(ai, bj, At, Bt) do { __builtin_amdgcn_s_setprio(1); _Pragma("unroll") for (int m = 0; m < 4; ++m) _Pragma("unroll") for (int n = 0; n < 2; ++n) _Pragma("unroll") for (int k = 0; k < 2; ++k) \
;         acc[ai][bj][m][n] = __builtin_amdgcn_mfma_f32_16x16x32_bf16(Bt[n][k], At[m][k], acc[ai][bj][m][n], 0, 0, 0); __builtin_amdgcn_s_setprio(0); } while (0)
; #define PG8_WAIT_V(n) asm volatile("s_waitcnt vmcnt(" #n ")" ::: "memory")
; #define PG8_WAIT_L(n) asm volatile("s_waitcnt lgkmcnt(" #n ")" ::: "memory")
; #define PG8_BAR __builtin_amdgcn_s_barrier()
; #define PG8_SCHED __builtin_amdgcn_sched_barrier(0)
; __device__ __forceinline__ void gemm_phase(const int tid, LAS unsigned char* lds, const Gemm g, const StaticOrder& S, const int mode  , void* Cout, const int ldc, float* rvs, const float* rbs, const float* rbs_tail) {
;     ...
;             PG8_WAIT_V(8); PG8_WAIT_L(0); PG8_BAR; PG8_MMA(0, 0, At, B0); PG8_MMA(0, 1, At, B1); PG8_BAR; PG8_SCHED;
;             PG8_LDA(At, 0, 1); PG8_STAGE(PG8_SB(0, 0), b2, voffB); PG8_STAGE(PG8_SB(0, 1), b2 + hstepB, voffB); PG8_STAGE(PG8_SA(0, 0), a2, voffA);
;             PG8_WAIT_V(8); PG8_WAIT_L(0); PG8_BAR; PG8_MMA(1, 0, At, B0); PG8_MMA(1, 1, At, B1); PG8_BAR; PG8_SCHED;
	v_mfma_f32_16x16x32_bf16 v[124:127], v[142:145], v[188:191], v[124:127]
	v_mfma_f32_16x16x32_bf16 v[120:123], v[154:157], v[188:191], v[120:123]
	v_mfma_f32_16x16x32_bf16 v[116:119], v[142:145], v[216:219], v[116:119]
	v_mfma_f32_16x16x32_bf16 v[112:115], v[154:157], v[216:219], v[112:115]
	v_mfma_f32_16x16x32_bf16 v[104:107], v[142:145], v[224:227], v[104:107]
	v_mfma_f32_16x16x32_bf16 v[96:99], v[154:157], v[224:227], v[96:99]
	v_mfma_f32_16x16x32_bf16 v[88:91], v[142:145], v[232:235], v[88:91]
	v_mfma_f32_16x16x32_bf16 v[80:83], v[154:157], v[232:235], v[80:83]
	v_mfma_f32_16x16x32_bf16 v[124:127], v[150:153], v[212:215], v[124:127]
	v_mfma_f32_16x16x32_bf16 v[120:123], v[168:171], v[212:215], v[120:123]
	v_mfma_f32_16x16x32_bf16 v[116:119], v[150:153], v[220:223], v[116:119]
	v_mfma_f32_16x16x32_bf16 v[112:115], v[168:171], v[220:223], v[112:115]
	v_mfma_f32_16x16x32_bf16 v[104:107], v[150:153], v[228:231], v[104:107]
	v_mfma_f32_16x16x32_bf16 v[96:99], v[168:171], v[228:231], v[96:99]
	v_mfma_f32_16x16x32_bf16 v[88:91], v[150:153], v[236:239], v[88:91]
	v_mfma_f32_16x16x32_bf16 v[80:83], v[168:171], v[236:239], v[80:83]
	s_setprio 0
	s_setprio 1
	v_mfma_f32_16x16x32_bf16 v[108:111], v[172:175], v[188:191], v[108:111]
	v_mfma_f32_16x16x32_bf16 v[100:103], v[180:183], v[188:191], v[100:103]
	v_mfma_f32_16x16x32_bf16 v[92:95], v[172:175], v[216:219], v[92:95]
	v_mfma_f32_16x16x32_bf16 v[84:87], v[180:183], v[216:219], v[84:87]
	v_mfma_f32_16x16x32_bf16 v[76:79], v[172:175], v[224:227], v[76:79]
	v_mfma_f32_16x16x32_bf16 v[72:75], v[180:183], v[224:227], v[72:75]
	v_mfma_f32_16x16x32_bf16 v[68:71], v[172:175], v[232:235], v[68:71]
	v_mfma_f32_16x16x32_bf16 v[64:67], v[180:183], v[232:235], v[64:67]
	v_mfma_f32_16x16x32_bf16 v[108:111], v[176:179], v[212:215], v[108:111]
	v_mfma_f32_16x16x32_bf16 v[100:103], v[184:187], v[212:215], v[100:103]
	v_mfma_f32_16x16x32_bf16 v[92:95], v[176:179], v[220:223], v[92:95]
	v_mfma_f32_16x16x32_bf16 v[84:87], v[184:187], v[220:223], v[84:87]
	v_mfma_f32_16x16x32_bf16 v[76:79], v[176:179], v[228:231], v[76:79]
	v_mfma_f32_16x16x32_bf16 v[72:75], v[184:187], v[228:231], v[72:75]
	v_mfma_f32_16x16x32_bf16 v[68:71], v[176:179], v[236:239], v[68:71]
	v_mfma_f32_16x16x32_bf16 v[64:67], v[184:187], v[236:239], v[64:67]
	s_barrier
	s_setprio 0
	s_add_i32 s73, s73, s70
	v_lshl_add_u64 v[158:159], s[74:75], 0, v[160:161]
	s_mov_b32 m0, s73
	ds_read_b128 v[188:191], v149 offset:16384
	ds_read_b128 v[212:215], v149 offset:17408
	ds_read_b128 v[216:219], v149 offset:18432
	ds_read_b128 v[220:223], v149 offset:19456
	ds_read_b128 v[224:227], v149 offset:20480
	ds_read_b128 v[228:231], v149 offset:21504
	ds_read_b128 v[232:235], v149 offset:22528
	ds_read_b128 v[236:239], v149 offset:23552
	global_load_lds_dwordx4 v[158:159], off
	s_add_i32 m0, s73, 0x2000
	v_lshl_add_u64 v[192:193], s[74:75], 0, v[132:133]
	s_add_u32 s74, s74, s59
	s_addc_u32 s75, s75, 0
	s_add_i32 s68, s68, s70
	global_load_lds_dwordx4 v[192:193], off
	v_lshl_add_u64 v[194:195], s[74:75], 0, v[160:161]
	s_mov_b32 m0, s68
	v_lshl_add_u64 v[240:241], s[74:75], 0, v[132:133]
	global_load_lds_dwordx4 v[194:195], off
	s_add_i32 m0, s68, 0x2000
	v_lshl_add_u64 v[242:243], s[62:63], 0, v[128:129]
	global_load_lds_dwordx4 v[240:241], off
	s_mov_b32 m0, s71
	v_lshl_add_u64 v[244:245], s[62:63], 0, v[130:131]
	global_load_lds_dwordx4 v[242:243], off
	s_mov_b32 m0, s88
	s_nop 0
	global_load_lds_dwordx4 v[244:245], off
	s_nop 0
	s_setprio 1
	s_waitcnt vmcnt(8)
	s_waitcnt lgkmcnt(0)
	s_barrier
	v_mfma_f32_16x16x32_bf16 v[60:63], v[142:145], v[188:191], v[60:63]
	v_mfma_f32_16x16x32_bf16 v[56:59], v[154:157], v[188:191], v[56:59]
	v_mfma_f32_16x16x32_bf16 v[52:55], v[142:145], v[216:219], v[52:55]
	v_mfma_f32_16x16x32_bf16 v[48:51], v[154:157], v[216:219], v[48:51]
	v_mfma_f32_16x16x32_bf16 v[36:39], v[142:145], v[224:227], v[36:39]
	v_mfma_f32_16x16x32_bf16 v[32:35], v[154:157], v[224:227], v[32:35]
	v_mfma_f32_16x16x32_bf16 v[20:23], v[142:145], v[232:235], v[20:23]
	v_mfma_f32_16x16x32_bf16 v[16:19], v[154:157], v[232:235], v[16:19]
	v_mfma_f32_16x16x32_bf16 v[60:63], v[150:153], v[212:215], v[60:63]
	v_mfma_f32_16x16x32_bf16 v[56:59], v[168:171], v[212:215], v[56:59]
	v_mfma_f32_16x16x32_bf16 v[52:55], v[150:153], v[220:223], v[52:55]
	v_mfma_f32_16x16x32_bf16 v[48:51], v[168:171], v[220:223], v[48:51]
	v_mfma_f32_16x16x32_bf16 v[36:39], v[150:153], v[228:231], v[36:39]
	v_mfma_f32_16x16x32_bf16 v[32:35], v[168:171], v[228:231], v[32:35]
	v_mfma_f32_16x16x32_bf16 v[20:23], v[150:153], v[236:239], v[20:23]
	v_mfma_f32_16x16x32_bf16 v[16:19], v[168:171], v[236:239], v[16:19]
	s_setprio 0
	s_setprio 1
	v_mfma_f32_16x16x32_bf16 v[44:47], v[172:175], v[188:191], v[44:47]
	v_mfma_f32_16x16x32_bf16 v[40:43], v[180:183], v[188:191], v[40:43]
	v_mfma_f32_16x16x32_bf16 v[28:31], v[172:175], v[216:219], v[28:31]
	v_mfma_f32_16x16x32_bf16 v[24:27], v[180:183], v[216:219], v[24:27]
	v_mfma_f32_16x16x32_bf16 v[12:15], v[172:175], v[224:227], v[12:15]
	v_mfma_f32_16x16x32_bf16 v[8:11], v[180:183], v[224:227], v[8:11]
	v_mfma_f32_16x16x32_bf16 v[4:7], v[172:175], v[232:235], v[4:7]
	v_mfma_f32_16x16x32_bf16 v[0:3], v[180:183], v[232:235], v[0:3]
	v_mfma_f32_16x16x32_bf16 v[44:47], v[176:179], v[212:215], v[44:47]
	v_mfma_f32_16x16x32_bf16 v[40:43], v[184:187], v[212:215], v[40:43]
	v_mfma_f32_16x16x32_bf16 v[28:31], v[176:179], v[220:223], v[28:31]
	v_mfma_f32_16x16x32_bf16 v[24:27], v[184:187], v[220:223], v[24:27]
	v_mfma_f32_16x16x32_bf16 v[12:15], v[176:179], v[228:231], v[12:15]
	v_mfma_f32_16x16x32_bf16 v[8:11], v[184:187], v[228:231], v[8:11]
	v_mfma_f32_16x16x32_bf16 v[4:7], v[176:179], v[236:239], v[4:7]
	v_mfma_f32_16x16x32_bf16 v[0:3], v[184:187], v[236:239], v[0:3]
	s_barrier
; #define PG8_STAGE(bufoff, gbase, voff) do { _Pragma("unroll") for (int _i = 0; _i < 2; ++_i) \
;         __builtin_amdgcn_global_load_lds((const unsigned*)((const char*)(gbase) + (voff)[_i]), (LAS unsigned*)(lds + (bufoff) + ldsw + _i * 8192), 16, 0, 0); } while (0)
; #define PG8_LDA(dst, b, h) do { _Pragma("unroll") for (int m = 0; m < 4; ++m) _Pragma("unroll") for (int k = 0; k < 2; ++k) dst[m][k] = *(const LAS bf16x8*)(lds + PG8_SA(b, h) + aoff + m * 2048 + k * 1024); } while (0)
; #define PG8_LDB(dst, b, h) do { _Pragma("unroll") for (int n = 0; n < 2; ++n) _Pragma("unroll") for (int k = 0; k < 2; ++k) dst[n][k] = *(const LAS bf16x8*)(lds + PG8_SB(b, h) + boff + n * 2048 + k * 1024); } while (0)
; #define PG8_MMA(ai, bj, At, Bt) do { __builtin_amdgcn_s_setprio(1); _Pragma("unroll") for (int m = 0; m < 4; ++m) _Pragma("unroll") for (int n = 0; n < 2; ++n) _Pragma("unroll") for (int k = 0; k < 2; ++k) \
;         acc[ai][bj][m][n] = __builtin_amdgcn_mfma_f32_16x16x32_bf16(Bt[n][k], At[m][k], acc[ai][bj][m][n], 0, 0, 0); __builtin_amdgcn_s_setprio(0); } while (0)
; #define PG8_WAIT_V(n) asm volatile("s_waitcnt vmcnt(" #n ")" ::: "memory")
; #define PG8_WAIT_L(n) asm volatile("s_waitcnt lgkmcnt(" #n ")" ::: "memory")
; #define PG8_BAR __builtin_amdgcn_s_barrier()
; #define PG8_SCHED __builtin_amdgcn_sched_barrier(0)
; __device__ __forceinline__ void gemm_phase(const int tid, LAS unsigned char* lds, const Gemm g, const StaticOrder& S, const int mode  , void* Cout, const int ldc, float* rvs, const float* rbs, const float* rbs_tail) {
;     ...
;             PG8_LDB(B0, 1, 0); PG8_LDB(B1, 1, 1); PG8_SCHED; PG8_LDA(At, 1, 0); PG8_STAGE(PG8_SA(0, 1), a2 + hstepA, voffA);
;             PG8_WAIT_V(8); PG8_WAIT_L(0); PG8_BAR; PG8_MMA(0, 0, At, B0); PG8_MMA(0, 1, At, B1); PG8_BAR; PG8_SCHED;
	s_setprio 0
	s_add_i32 s68, 0, 0x18000
	v_add_u32_e32 v165, s68, v147
	s_add_i32 s73, 0, 0x1c000
	ds_read_b128 v[142:145], v165
	ds_read_b128 v[150:153], v165 offset:1024
	ds_read_b128 v[154:157], v165 offset:2048
	ds_read_b128 v[168:171], v165 offset:3072
	v_add_u32_e32 v165, s73, v147
	ds_read_b128 v[172:175], v165
	ds_read_b128 v[176:179], v165 offset:1024
	ds_read_b128 v[180:183], v165 offset:2048
	ds_read_b128 v[184:187], v165 offset:3072
	s_add_u32 s62, s62, s46
	s_addc_u32 s63, s63, 0
	s_mov_b32 m0, s89
	v_lshl_add_u64 v[246:247], s[62:63], 0, v[128:129]
	ds_read_b128 v[188:191], v149 offset:32768
	ds_read_b128 v[212:215], v149 offset:33792
	ds_read_b128 v[216:219], v149 offset:34816
	ds_read_b128 v[220:223], v149 offset:35840
	ds_read_b128 v[224:227], v149 offset:36864
	ds_read_b128 v[228:231], v149 offset:37888
	ds_read_b128 v[232:235], v149 offset:38912
	ds_read_b128 v[236:239], v149 offset:39936
	global_load_lds_dwordx4 v[246:247], off
	v_lshl_add_u64 v[246:247], s[62:63], 0, v[130:131]
	s_mov_b32 m0, s90
	s_nop 0
	global_load_lds_dwordx4 v[246:247], off
	s_nop 0
	s_setprio 1
	s_waitcnt vmcnt(8)
	s_waitcnt lgkmcnt(0)
	s_barrier
	v_mfma_f32_16x16x32_bf16 v[124:127], v[142:145], v[188:191], v[124:127]
	v_mfma_f32_16x16x32_bf16 v[120:123], v[154:157], v[188:191], v[120:123]
	v_mfma_f32_16x16x32_bf16 v[116:119], v[142:145], v[216:219], v[116:119]
	v_mfma_f32_16x16x32_bf16 v[112:115], v[154:157], v[216:219], v[112:115]
	v_mfma_f32_16x16x32_bf16 v[104:107], v[142:145], v[224:227], v[104:107]
	v_mfma_f32_16x16x32_bf16 v[96:99], v[154:157], v[224:227], v[96:99]
	v_mfma_f32_16x16x32_bf16 v[88:91], v[142:145], v[232:235], v[88:91]
	v_mfma_f32_16x16x32_bf16 v[80:83], v[154:157], v[232:235], v[80:83]
	v_mfma_f32_16x16x32_bf16 v[124:127], v[150:153], v[212:215], v[124:127]
	v_mfma_f32_16x16x32_bf16 v[120:123], v[168:171], v[212:215], v[120:123]
	v_mfma_f32_16x16x32_bf16 v[116:119], v[150:153], v[220:223], v[116:119]
	v_mfma_f32_16x16x32_bf16 v[112:115], v[168:171], v[220:223], v[112:115]
	v_mfma_f32_16x16x32_bf16 v[104:107], v[150:153], v[228:231], v[104:107]
	v_mfma_f32_16x16x32_bf16 v[96:99], v[168:171], v[228:231], v[96:99]
	v_mfma_f32_16x16x32_bf16 v[88:91], v[150:153], v[236:239], v[88:91]
	v_mfma_f32_16x16x32_bf16 v[80:83], v[168:171], v[236:239], v[80:83]
	s_setprio 0
	s_setprio 1
	v_mfma_f32_16x16x32_bf16 v[108:111], v[172:175], v[188:191], v[108:111]
	v_mfma_f32_16x16x32_bf16 v[100:103], v[180:183], v[188:191], v[100:103]
	v_mfma_f32_16x16x32_bf16 v[92:95], v[172:175], v[216:219], v[92:95]
	v_mfma_f32_16x16x32_bf16 v[84:87], v[180:183], v[216:219], v[84:87]
	v_mfma_f32_16x16x32_bf16 v[76:79], v[172:175], v[224:227], v[76:79]
	v_mfma_f32_16x16x32_bf16 v[72:75], v[180:183], v[224:227], v[72:75]
	v_mfma_f32_16x16x32_bf16 v[68:71], v[172:175], v[232:235], v[68:71]
	v_mfma_f32_16x16x32_bf16 v[64:67], v[180:183], v[232:235], v[64:67]
	v_mfma_f32_16x16x32_bf16 v[108:111], v[176:179], v[212:215], v[108:111]
	v_mfma_f32_16x16x32_bf16 v[100:103], v[184:187], v[212:215], v[100:103]
	v_mfma_f32_16x16x32_bf16 v[92:95], v[176:179], v[220:223], v[92:95]
	v_mfma_f32_16x16x32_bf16 v[84:87], v[184:187], v[220:223], v[84:87]
	v_mfma_f32_16x16x32_bf16 v[76:79], v[176:179], v[228:231], v[76:79]
	v_mfma_f32_16x16x32_bf16 v[72:75], v[184:187], v[228:231], v[72:75]
	v_mfma_f32_16x16x32_bf16 v[68:71], v[176:179], v[236:239], v[68:71]
	v_mfma_f32_16x16x32_bf16 v[64:67], v[184:187], v[236:239], v[64:67]
	s_barrier
; #define PG8_STAGE(bufoff, gbase, voff) do { _Pragma("unroll") for (int _i = 0; _i < 2; ++_i) \
;         __builtin_amdgcn_global_load_lds((const unsigned*)((const char*)(gbase) + (voff)[_i]), (LAS unsigned*)(lds + (bufoff) + ldsw + _i * 8192), 16, 0, 0); } while (0)
; #define PG8_LDA(dst, b, h) do { _Pragma("unroll") for (int m = 0; m < 4; ++m) _Pragma("unroll") for (int k = 0; k < 2; ++k) dst[m][k] = *(const LAS bf16x8*)(lds + PG8_SA(b, h) + aoff + m * 2048 + k * 1024); } while (0)
; #define PG8_MMA(ai, bj, At, Bt) do { __builtin_amdgcn_s_setprio(1); _Pragma("unroll") for (int m = 0; m < 4; ++m) _Pragma("unroll") for (int n = 0; n < 2; ++n) _Pragma("unroll") for (int k = 0; k < 2; ++k) \
;         acc[ai][bj][m][n] = __builtin_amdgcn_mfma_f32_16x16x32_bf16(Bt[n][k], At[m][k], acc[ai][bj][m][n], 0, 0, 0); __builtin_amdgcn_s_setprio(0); } while (0)
; #define PG8_WAIT_V(n) asm volatile("s_waitcnt vmcnt(" #n ")" ::: "memory")
; #define PG8_WAIT_L(n) asm volatile("s_waitcnt lgkmcnt(" #n ")" ::: "memory")
; #define PG8_BAR __builtin_amdgcn_s_barrier()
; #define PG8_SCHED __builtin_amdgcn_sched_barrier(0)
; __device__ __forceinline__ void gemm_phase(const int tid, LAS unsigned char* lds, const Gemm g, const StaticOrder& S, const int mode  , void* Cout, const int ldc, float* rvs, const float* rbs, const float* rbs_tail) {
;     ...
;             PG8_LDA(At, 1, 1); PG8_STAGE(PG8_SB(1, 0), b3, voffB); PG8_STAGE(PG8_SB(1, 1), b3 + hstepB, voffB); PG8_STAGE(PG8_SA(1, 0), a3, voffA);
;             PG8_WAIT_V(8); PG8_WAIT_L(0); PG8_BAR; PG8_MMA(1, 0, At, B0); PG8_MMA(1, 1, At, B1); PG8_BAR; PG8_SCHED;
;         }
	s_setprio 0
	s_add_i32 s62, s68, s70
	v_lshl_add_u64 v[158:159], v[158:159], 0, s[36:37]
	s_mov_b32 m0, s62
	ds_read_b128 v[188:191], v149 offset:49152
	ds_read_b128 v[212:215], v149 offset:50176
	ds_read_b128 v[216:219], v149 offset:51200
	ds_read_b128 v[220:223], v149 offset:52224
	ds_read_b128 v[224:227], v149 offset:53248
	ds_read_b128 v[228:231], v149 offset:54272
	ds_read_b128 v[232:235], v149 offset:55296
	ds_read_b128 v[236:239], v149 offset:56320
	global_load_lds_dwordx4 v[158:159], off
	v_lshl_add_u64 v[158:159], v[192:193], 0, s[36:37]
	s_add_i32 m0, s62, 0x2000
	s_add_i32 s62, s73, s70
	global_load_lds_dwordx4 v[158:159], off
	v_lshl_add_u64 v[158:159], v[194:195], 0, s[36:37]
	s_mov_b32 m0, s62
	s_nop 0
	global_load_lds_dwordx4 v[158:159], off
	v_lshl_add_u64 v[158:159], v[240:241], 0, s[36:37]
	s_add_i32 m0, s62, 0x2000
	s_nop 0
	global_load_lds_dwordx4 v[158:159], off
	v_lshl_add_u64 v[158:159], v[242:243], 0, s[36:37]
	s_mov_b32 m0, s91
	s_nop 0
	global_load_lds_dwordx4 v[158:159], off
	v_lshl_add_u64 v[158:159], v[244:245], 0, s[36:37]
	s_mov_b32 m0, s16
	s_nop 0
	global_load_lds_dwordx4 v[158:159], off
	s_nop 0
	s_setprio 1
	s_waitcnt vmcnt(8)
	s_waitcnt lgkmcnt(0)
	s_barrier
	v_mfma_f32_16x16x32_bf16 v[60:63], v[142:145], v[188:191], v[60:63]
	v_mfma_f32_16x16x32_bf16 v[56:59], v[154:157], v[188:191], v[56:59]
	v_mfma_f32_16x16x32_bf16 v[52:55], v[142:145], v[216:219], v[52:55]
	v_mfma_f32_16x16x32_bf16 v[48:51], v[154:157], v[216:219], v[48:51]
	v_mfma_f32_16x16x32_bf16 v[36:39], v[142:145], v[224:227], v[36:39]
	v_mfma_f32_16x16x32_bf16 v[32:35], v[154:157], v[224:227], v[32:35]
	v_mfma_f32_16x16x32_bf16 v[20:23], v[142:145], v[232:235], v[20:23]
	v_mfma_f32_16x16x32_bf16 v[16:19], v[154:157], v[232:235], v[16:19]
	v_mfma_f32_16x16x32_bf16 v[60:63], v[150:153], v[212:215], v[60:63]
	v_mfma_f32_16x16x32_bf16 v[56:59], v[168:171], v[212:215], v[56:59]
	v_mfma_f32_16x16x32_bf16 v[52:55], v[150:153], v[220:223], v[52:55]
	v_mfma_f32_16x16x32_bf16 v[48:51], v[168:171], v[220:223], v[48:51]
	v_mfma_f32_16x16x32_bf16 v[36:39], v[150:153], v[228:231], v[36:39]
	v_mfma_f32_16x16x32_bf16 v[32:35], v[168:171], v[228:231], v[32:35]
	v_mfma_f32_16x16x32_bf16 v[20:23], v[150:153], v[236:239], v[20:23]
	v_mfma_f32_16x16x32_bf16 v[16:19], v[168:171], v[236:239], v[16:19]
	s_setprio 0
	s_setprio 1
	v_mfma_f32_16x16x32_bf16 v[44:47], v[172:175], v[188:191], v[44:47]
	v_mfma_f32_16x16x32_bf16 v[40:43], v[180:183], v[188:191], v[40:43]
	v_mfma_f32_16x16x32_bf16 v[28:31], v[172:175], v[216:219], v[28:31]
	v_mfma_f32_16x16x32_bf16 v[24:27], v[180:183], v[216:219], v[24:27]
	v_mfma_f32_16x16x32_bf16 v[12:15], v[172:175], v[224:227], v[12:15]
	v_mfma_f32_16x16x32_bf16 v[8:11], v[180:183], v[224:227], v[8:11]
	v_mfma_f32_16x16x32_bf16 v[4:7], v[172:175], v[232:235], v[4:7]
	v_mfma_f32_16x16x32_bf16 v[0:3], v[180:183], v[232:235], v[0:3]
	v_mfma_f32_16x16x32_bf16 v[44:47], v[176:179], v[212:215], v[44:47]
	v_mfma_f32_16x16x32_bf16 v[40:43], v[184:187], v[212:215], v[40:43]
	v_mfma_f32_16x16x32_bf16 v[28:31], v[176:179], v[220:223], v[28:31]
	v_mfma_f32_16x16x32_bf16 v[24:27], v[184:187], v[220:223], v[24:27]
	v_mfma_f32_16x16x32_bf16 v[12:15], v[176:179], v[228:231], v[12:15]
	v_mfma_f32_16x16x32_bf16 v[8:11], v[184:187], v[228:231], v[8:11]
	v_mfma_f32_16x16x32_bf16 v[4:7], v[176:179], v[236:239], v[4:7]
	v_mfma_f32_16x16x32_bf16 v[0:3], v[184:187], v[236:239], v[0:3]
	s_barrier
	s_setprio 0
	s_add_u32 s60, s60, 0x100
	s_addc_u32 s61, s61, 0
	s_add_u32 s45, s45, 0x100
	s_addc_u32 s53, s53, 0
	s_cmp_ge_u32 s72, s3
	s_mov_b32 s68, s72
	s_cbranch_scc0 .LBB0_231
